# write-through sc1 also for merge, carry fix, branch-A conv and weight conversion stores; L2 write-back walk only after phases 0 3 5 10
# speedup vs baseline: 1.0685x; 1.0053x over previous
.LBB0_105:
	s_or_b64 exec, exec, s[2:3]
	s_waitcnt vmcnt(0)
	v_lshlrev_b32_e32 v0, 16, v54
	v_mul_f32_e32 v0, 0xbfb8aa3b, v0
	s_waitcnt vmcnt(2)
	v_lshlrev_b32_e32 v90, 16, v50
	v_exp_f32_e32 v0, v0
	v_mul_f32_e32 v90, 0xbfb8aa3b, v90
	v_exp_f32_e32 v91, v90
	v_and_b32_e32 v50, 0xffff0000, v50
	v_add_f32_e32 v0, 1.0, v0
	v_rcp_f32_e32 v90, v0
	v_add_f32_e32 v0, 1.0, v91
	v_rcp_f32_e32 v91, v0
	v_and_b32_e32 v0, 0xffff0000, v54
	v_mul_f32_e32 v0, 0xbfb8aa3b, v0
	v_exp_f32_e32 v0, v0
	v_mul_f32_e32 v50, 0xbfb8aa3b, v50
	v_exp_f32_e32 v50, v50
	s_waitcnt vmcnt(0)
	v_lshlrev_b32_e32 v93, 16, v62
	v_lshlrev_b32_e32 v92, 16, v58
	v_add_f32_e32 v0, 1.0, v0
	v_pk_mul_f32 v[90:91], v[90:91], v[92:93]
	v_rcp_f32_e32 v92, v0
	v_add_f32_e32 v0, 1.0, v50
	v_rcp_f32_e32 v93, v0
	v_lshlrev_b32_e32 v54, 16, v55
	v_add_f32_e32 v0, v90, v91
	v_and_b32_e32 v90, 0xffff0000, v58
	v_mul_f32_e32 v54, 0xbfb8aa3b, v54
	v_lshlrev_b32_e32 v58, 16, v51
	v_exp_f32_e32 v54, v54
	v_mul_f32_e32 v58, 0xbfb8aa3b, v58
	v_and_b32_e32 v91, 0xffff0000, v62
	v_exp_f32_e32 v58, v58
	v_pk_mul_f32 v[90:91], v[92:93], v[90:91]
	v_and_b32_e32 v51, 0xffff0000, v51
	v_add_f32_e32 v50, v90, v91
	v_cvt_pk_bf16_f32 v50, v0, v50
	v_add_f32_e32 v0, 1.0, v54
	v_rcp_f32_e32 v90, v0
	v_add_f32_e32 v0, 1.0, v58
	v_rcp_f32_e32 v91, v0
	v_and_b32_e32 v0, 0xffff0000, v55
	v_mul_f32_e32 v0, 0xbfb8aa3b, v0
	v_exp_f32_e32 v0, v0
	v_mul_f32_e32 v51, 0xbfb8aa3b, v51
	v_exp_f32_e32 v51, v51
	v_lshlrev_b32_e32 v93, 16, v63
	v_lshlrev_b32_e32 v92, 16, v59
	v_add_f32_e32 v0, 1.0, v0
	v_pk_mul_f32 v[54:55], v[90:91], v[92:93]
	v_rcp_f32_e32 v90, v0
	v_add_f32_e32 v0, 1.0, v51
	v_rcp_f32_e32 v91, v0
	v_add_f32_e32 v0, v54, v55
	v_and_b32_e32 v55, 0xffff0000, v63
	v_and_b32_e32 v54, 0xffff0000, v59
	v_pk_mul_f32 v[54:55], v[90:91], v[54:55]
	v_lshlrev_b32_e32 v59, 16, v64
	v_add_f32_e32 v51, v54, v55
	v_lshlrev_b32_e32 v54, 16, v56
	v_mul_f32_e32 v54, 0xbfb8aa3b, v54
	v_lshlrev_b32_e32 v55, 16, v52
	v_exp_f32_e32 v54, v54
	v_mul_f32_e32 v55, 0xbfb8aa3b, v55
	v_exp_f32_e32 v55, v55
	v_cvt_pk_bf16_f32 v51, v0, v51
	v_add_f32_e32 v0, 1.0, v54
	v_rcp_f32_e32 v54, v0
	v_add_f32_e32 v0, 1.0, v55
	v_rcp_f32_e32 v55, v0
	v_and_b32_e32 v0, 0xffff0000, v56
	v_mul_f32_e32 v0, 0xbfb8aa3b, v0
	v_and_b32_e32 v52, 0xffff0000, v52
	v_exp_f32_e32 v0, v0
	v_mul_f32_e32 v52, 0xbfb8aa3b, v52
	v_exp_f32_e32 v52, v52
	v_lshlrev_b32_e32 v58, 16, v60
	v_add_f32_e32 v0, 1.0, v0
	v_pk_mul_f32 v[54:55], v[54:55], v[58:59]
	v_rcp_f32_e32 v58, v0
	v_add_f32_e32 v0, 1.0, v52
	v_rcp_f32_e32 v59, v0
	v_add_f32_e32 v0, v54, v55
	v_and_b32_e32 v55, 0xffff0000, v64
	v_and_b32_e32 v54, 0xffff0000, v60
	v_pk_mul_f32 v[54:55], v[58:59], v[54:55]
	v_lshlrev_b32_e32 v59, 16, v65
	v_add_f32_e32 v52, v54, v55
	v_lshlrev_b32_e32 v54, 16, v57
	v_mul_f32_e32 v54, 0xbfb8aa3b, v54
	v_lshlrev_b32_e32 v55, 16, v53
	v_exp_f32_e32 v54, v54
	v_mul_f32_e32 v55, 0xbfb8aa3b, v55
	v_exp_f32_e32 v55, v55
	v_cvt_pk_bf16_f32 v52, v0, v52
	v_add_f32_e32 v0, 1.0, v54
	v_rcp_f32_e32 v54, v0
	v_add_f32_e32 v0, 1.0, v55
	v_rcp_f32_e32 v55, v0
	v_and_b32_e32 v0, 0xffff0000, v57
	v_mul_f32_e32 v0, 0xbfb8aa3b, v0
	v_and_b32_e32 v53, 0xffff0000, v53
	v_exp_f32_e32 v0, v0
	v_mul_f32_e32 v53, 0xbfb8aa3b, v53
	v_exp_f32_e32 v53, v53
	v_lshlrev_b32_e32 v58, 16, v61
	v_add_f32_e32 v0, 1.0, v0
	v_rcp_f32_e32 v56, v0
	v_add_f32_e32 v0, 1.0, v53
	v_rcp_f32_e32 v57, v0
	v_pk_mul_f32 v[54:55], v[54:55], v[58:59]
	s_nop 0
	v_add_f32_e32 v0, v54, v55
	v_and_b32_e32 v55, 0xffff0000, v65
	v_and_b32_e32 v54, 0xffff0000, v61
	v_pk_mul_f32 v[54:55], v[56:57], v[54:55]
	s_nop 0
	v_add_f32_e32 v53, v54, v55
	v_lshl_add_u64 v[54:55], v[68:69], 0, s[46:47]
	v_cvt_pk_bf16_f32 v53, v0, v53
	global_store_dwordx4 v[54:55], v[50:53], off sc1
	s_and_saveexec_b64 s[2:3], s[42:43]
	s_cbranch_execz .LBB0_108
	v_lshlrev_b32_e32 v0, 16, v2
	v_mul_f32_e32 v0, 0xbfb8aa3b, v0
	v_exp_f32_e32 v0, v0
	v_lshlrev_b32_e32 v53, 16, v38
	v_lshlrev_b32_e32 v52, 16, v26
	v_lshlrev_b32_e32 v55, 16, v39
	v_add_f32_e32 v0, 1.0, v0
	v_rcp_f32_e32 v50, v0
	v_lshlrev_b32_e32 v0, 16, v14
	v_mul_f32_e32 v0, 0xbfb8aa3b, v0
	v_exp_f32_e32 v0, v0
	v_lshlrev_b32_e32 v54, 16, v27
	v_lshlrev_b32_e32 v57, 16, v41
	v_lshlrev_b32_e32 v56, 16, v29
	v_add_f32_e32 v0, 1.0, v0
	v_rcp_f32_e32 v51, v0
	s_nop 0
	v_pk_mul_f32 v[50:51], v[50:51], v[52:53]
	s_nop 0
	v_add_f32_e32 v0, v50, v51
	v_and_b32_e32 v50, 0xffff0000, v2
	v_and_b32_e32 v51, 0xffff0000, v14
	v_mul_f32_e32 v50, 0xbfb8aa3b, v50
	v_mul_f32_e32 v51, 0xbfb8aa3b, v51
	v_exp_f32_e32 v50, v50
	v_exp_f32_e32 v51, v51
	v_and_b32_e32 v53, 0xffff0000, v38
	v_and_b32_e32 v52, 0xffff0000, v26
	v_add_f32_e32 v50, 1.0, v50
	v_add_f32_e32 v51, 1.0, v51
	v_rcp_f32_e32 v50, v50
	v_rcp_f32_e32 v51, v51
	s_nop 0
	v_pk_mul_f32 v[50:51], v[50:51], v[52:53]
	s_nop 0
	v_add_f32_e32 v50, v50, v51
	v_cvt_pk_bf16_f32 v50, v0, v50
	v_lshlrev_b32_e32 v0, 16, v3
	v_mul_f32_e32 v0, 0xbfb8aa3b, v0
	v_exp_f32_e32 v0, v0
	v_and_b32_e32 v51, 0xffff0000, v3
	v_mul_f32_e32 v51, 0xbfb8aa3b, v51
	v_exp_f32_e32 v51, v51
	v_add_f32_e32 v0, 1.0, v0
	v_rcp_f32_e32 v52, v0
	v_lshlrev_b32_e32 v0, 16, v15
	v_mul_f32_e32 v0, 0xbfb8aa3b, v0
	v_exp_f32_e32 v0, v0
	v_add_f32_e32 v51, 1.0, v51
	v_add_f32_e32 v0, 1.0, v0
	v_rcp_f32_e32 v53, v0
	s_nop 0
	v_pk_mul_f32 v[52:53], v[52:53], v[54:55]
	s_nop 0
	v_add_f32_e32 v0, v52, v53
	v_rcp_f32_e32 v52, v51
	v_and_b32_e32 v51, 0xffff0000, v15
	v_mul_f32_e32 v51, 0xbfb8aa3b, v51
	v_exp_f32_e32 v51, v51
	v_and_b32_e32 v55, 0xffff0000, v39
	v_and_b32_e32 v54, 0xffff0000, v27
	v_add_f32_e32 v51, 1.0, v51
	v_rcp_f32_e32 v53, v51
	s_nop 0
	v_pk_mul_f32 v[52:53], v[52:53], v[54:55]
	s_nop 0
	v_add_f32_e32 v51, v52, v53
	v_cvt_pk_bf16_f32 v51, v0, v51
	v_lshlrev_b32_e32 v0, 16, v4
	v_mul_f32_e32 v0, 0xbfb8aa3b, v0
	v_exp_f32_e32 v0, v0
	v_lshlrev_b32_e32 v55, 16, v40
	v_lshlrev_b32_e32 v54, 16, v28
	v_add_f32_e32 v0, 1.0, v0
	v_rcp_f32_e32 v52, v0
	v_lshlrev_b32_e32 v0, 16, v16
	v_mul_f32_e32 v0, 0xbfb8aa3b, v0
	v_exp_f32_e32 v0, v0
	s_nop 0
	v_add_f32_e32 v0, 1.0, v0
	v_rcp_f32_e32 v53, v0
	s_nop 0
	v_pk_mul_f32 v[52:53], v[52:53], v[54:55]
	s_nop 0
	v_add_f32_e32 v0, v52, v53
	v_and_b32_e32 v52, 0xffff0000, v4
	v_and_b32_e32 v53, 0xffff0000, v16
	v_mul_f32_e32 v52, 0xbfb8aa3b, v52
	v_mul_f32_e32 v53, 0xbfb8aa3b, v53
	v_exp_f32_e32 v52, v52
	v_exp_f32_e32 v53, v53
	v_and_b32_e32 v55, 0xffff0000, v40
	v_and_b32_e32 v54, 0xffff0000, v28
	v_add_f32_e32 v52, 1.0, v52
	v_add_f32_e32 v53, 1.0, v53
	v_rcp_f32_e32 v52, v52
	v_rcp_f32_e32 v53, v53
	s_nop 0
	v_pk_mul_f32 v[52:53], v[52:53], v[54:55]
	s_nop 0
	v_add_f32_e32 v52, v52, v53
	v_cvt_pk_bf16_f32 v52, v0, v52
	v_lshlrev_b32_e32 v0, 16, v5
	v_mul_f32_e32 v0, 0xbfb8aa3b, v0
	v_exp_f32_e32 v0, v0
	v_and_b32_e32 v53, 0xffff0000, v5
	v_mul_f32_e32 v53, 0xbfb8aa3b, v53
	v_exp_f32_e32 v53, v53
	v_add_f32_e32 v0, 1.0, v0
	v_rcp_f32_e32 v54, v0
	v_lshlrev_b32_e32 v0, 16, v17
	v_mul_f32_e32 v0, 0xbfb8aa3b, v0
	v_exp_f32_e32 v0, v0
	v_add_f32_e32 v53, 1.0, v53
	v_add_f32_e32 v0, 1.0, v0
	v_rcp_f32_e32 v55, v0
	s_nop 0
	v_pk_mul_f32 v[54:55], v[54:55], v[56:57]
	s_nop 0
	v_add_f32_e32 v0, v54, v55
	v_rcp_f32_e32 v54, v53
	v_and_b32_e32 v53, 0xffff0000, v17
	v_mul_f32_e32 v53, 0xbfb8aa3b, v53
	v_exp_f32_e32 v53, v53
	v_and_b32_e32 v57, 0xffff0000, v41
	v_and_b32_e32 v56, 0xffff0000, v29
	v_add_f32_e32 v53, 1.0, v53
	v_rcp_f32_e32 v55, v53
	s_nop 0
	v_pk_mul_f32 v[54:55], v[54:55], v[56:57]
	s_nop 0
	v_add_f32_e32 v53, v54, v55
	v_lshl_add_u64 v[54:55], v[82:83], 0, s[46:47]
	v_cvt_pk_bf16_f32 v53, v0, v53
	global_store_dwordx4 v[54:55], v[50:53], off sc1
	s_or_b64 exec, exec, s[2:3]
	s_and_saveexec_b64 s[2:3], s[0:1]
	s_cbranch_execnz .LBB0_109

.LBB0_109:
	v_lshlrev_b32_e32 v0, 16, v10
	v_mul_f32_e32 v0, 0xbfb8aa3b, v0
	v_exp_f32_e32 v0, v0
	v_lshlrev_b32_e32 v53, 16, v46
	v_lshlrev_b32_e32 v52, 16, v34
	v_lshlrev_b32_e32 v55, 16, v47
	v_add_f32_e32 v0, 1.0, v0
	v_rcp_f32_e32 v50, v0
	v_lshlrev_b32_e32 v0, 16, v22
	v_mul_f32_e32 v0, 0xbfb8aa3b, v0
	v_exp_f32_e32 v0, v0
	v_lshlrev_b32_e32 v54, 16, v35
	v_lshlrev_b32_e32 v57, 16, v49
	v_lshlrev_b32_e32 v56, 16, v37
	v_add_f32_e32 v0, 1.0, v0
	v_rcp_f32_e32 v51, v0
	s_nop 0
	v_pk_mul_f32 v[50:51], v[50:51], v[52:53]
	s_nop 0
	v_add_f32_e32 v0, v50, v51
	v_and_b32_e32 v50, 0xffff0000, v10
	v_and_b32_e32 v51, 0xffff0000, v22
	v_mul_f32_e32 v50, 0xbfb8aa3b, v50
	v_mul_f32_e32 v51, 0xbfb8aa3b, v51
	v_exp_f32_e32 v50, v50
	v_exp_f32_e32 v51, v51
	v_and_b32_e32 v53, 0xffff0000, v46
	v_and_b32_e32 v52, 0xffff0000, v34
	v_add_f32_e32 v50, 1.0, v50
	v_add_f32_e32 v51, 1.0, v51
	v_rcp_f32_e32 v50, v50
	v_rcp_f32_e32 v51, v51
	s_nop 0
	v_pk_mul_f32 v[50:51], v[50:51], v[52:53]
	s_nop 0
	v_add_f32_e32 v50, v50, v51
	v_cvt_pk_bf16_f32 v50, v0, v50
	v_lshlrev_b32_e32 v0, 16, v11
	v_mul_f32_e32 v0, 0xbfb8aa3b, v0
	v_exp_f32_e32 v0, v0
	v_and_b32_e32 v51, 0xffff0000, v11
	v_mul_f32_e32 v51, 0xbfb8aa3b, v51
	v_exp_f32_e32 v51, v51
	v_add_f32_e32 v0, 1.0, v0
	v_rcp_f32_e32 v52, v0
	v_lshlrev_b32_e32 v0, 16, v23
	v_mul_f32_e32 v0, 0xbfb8aa3b, v0
	v_exp_f32_e32 v0, v0
	v_add_f32_e32 v51, 1.0, v51
	v_add_f32_e32 v0, 1.0, v0
	v_rcp_f32_e32 v53, v0
	s_nop 0
	v_pk_mul_f32 v[52:53], v[52:53], v[54:55]
	s_nop 0
	v_add_f32_e32 v0, v52, v53
	v_rcp_f32_e32 v52, v51
	v_and_b32_e32 v51, 0xffff0000, v23
	v_mul_f32_e32 v51, 0xbfb8aa3b, v51
	v_exp_f32_e32 v51, v51
	v_and_b32_e32 v55, 0xffff0000, v47
	v_and_b32_e32 v54, 0xffff0000, v35
	v_add_f32_e32 v51, 1.0, v51
	v_rcp_f32_e32 v53, v51
	s_nop 0
	v_pk_mul_f32 v[52:53], v[52:53], v[54:55]
	s_nop 0
	v_add_f32_e32 v51, v52, v53
	v_cvt_pk_bf16_f32 v51, v0, v51
	v_lshlrev_b32_e32 v0, 16, v12
	v_mul_f32_e32 v0, 0xbfb8aa3b, v0
	v_exp_f32_e32 v0, v0
	v_lshlrev_b32_e32 v55, 16, v48
	v_lshlrev_b32_e32 v54, 16, v36
	v_add_f32_e32 v0, 1.0, v0
	v_rcp_f32_e32 v52, v0
	v_lshlrev_b32_e32 v0, 16, v24
	v_mul_f32_e32 v0, 0xbfb8aa3b, v0
	v_exp_f32_e32 v0, v0
	s_nop 0
	v_add_f32_e32 v0, 1.0, v0
	v_rcp_f32_e32 v53, v0
	s_nop 0
	v_pk_mul_f32 v[52:53], v[52:53], v[54:55]
	s_nop 0
	v_add_f32_e32 v0, v52, v53
	v_and_b32_e32 v52, 0xffff0000, v12
	v_and_b32_e32 v53, 0xffff0000, v24
	v_mul_f32_e32 v52, 0xbfb8aa3b, v52
	v_mul_f32_e32 v53, 0xbfb8aa3b, v53
	v_exp_f32_e32 v52, v52
	v_exp_f32_e32 v53, v53
	v_and_b32_e32 v55, 0xffff0000, v48
	v_and_b32_e32 v54, 0xffff0000, v36
	v_add_f32_e32 v52, 1.0, v52
	v_add_f32_e32 v53, 1.0, v53
	v_rcp_f32_e32 v52, v52
	v_rcp_f32_e32 v53, v53
	s_nop 0
	v_pk_mul_f32 v[52:53], v[52:53], v[54:55]
	s_nop 0
	v_add_f32_e32 v52, v52, v53
	v_cvt_pk_bf16_f32 v52, v0, v52
	v_lshlrev_b32_e32 v0, 16, v13
	v_mul_f32_e32 v0, 0xbfb8aa3b, v0
	v_exp_f32_e32 v0, v0
	v_and_b32_e32 v53, 0xffff0000, v13
	v_mul_f32_e32 v53, 0xbfb8aa3b, v53
	v_exp_f32_e32 v53, v53
	v_add_f32_e32 v0, 1.0, v0
	v_rcp_f32_e32 v54, v0
	v_lshlrev_b32_e32 v0, 16, v25
	v_mul_f32_e32 v0, 0xbfb8aa3b, v0
	v_exp_f32_e32 v0, v0
	v_add_f32_e32 v53, 1.0, v53
	v_add_f32_e32 v0, 1.0, v0
	v_rcp_f32_e32 v55, v0
	s_nop 0
	v_pk_mul_f32 v[54:55], v[54:55], v[56:57]
	s_nop 0
	v_add_f32_e32 v0, v54, v55
	v_rcp_f32_e32 v54, v53
	v_and_b32_e32 v53, 0xffff0000, v25
	v_mul_f32_e32 v53, 0xbfb8aa3b, v53
	v_exp_f32_e32 v53, v53
	v_and_b32_e32 v57, 0xffff0000, v49
	v_and_b32_e32 v56, 0xffff0000, v37
	v_add_f32_e32 v53, 1.0, v53
	v_rcp_f32_e32 v55, v53
	s_nop 0
	v_pk_mul_f32 v[54:55], v[54:55], v[56:57]
	s_nop 0
	v_add_f32_e32 v53, v54, v55
	v_lshl_add_u64 v[54:55], v[74:75], 0, s[46:47]
	v_cvt_pk_bf16_f32 v53, v0, v53
	global_store_dwordx4 v[54:55], v[50:53], off sc1
	s_or_b64 exec, exec, s[2:3]
	s_and_saveexec_b64 s[0:1], s[38:39]
	s_cbranch_execz .LBB0_98
.LBB0_110:
	v_lshlrev_b32_e32 v0, 16, v6
	v_mul_f32_e32 v0, 0xbfb8aa3b, v0
	v_exp_f32_e32 v0, v0
	v_lshlrev_b32_e32 v53, 16, v42
	v_lshlrev_b32_e32 v52, 16, v30
	v_lshlrev_b32_e32 v55, 16, v43
	v_add_f32_e32 v0, 1.0, v0
	v_rcp_f32_e32 v50, v0
	v_lshlrev_b32_e32 v0, 16, v18
	v_mul_f32_e32 v0, 0xbfb8aa3b, v0
	v_exp_f32_e32 v0, v0
	s_waitcnt lgkmcnt(0)
	v_lshlrev_b32_e32 v54, 16, v31
	v_lshlrev_b32_e32 v57, 16, v45
	v_lshlrev_b32_e32 v56, 16, v33
	v_add_f32_e32 v0, 1.0, v0
	v_rcp_f32_e32 v51, v0
	s_nop 0
	v_pk_mul_f32 v[50:51], v[50:51], v[52:53]
	s_nop 0
	v_add_f32_e32 v0, v50, v51
	v_and_b32_e32 v50, 0xffff0000, v6
	v_and_b32_e32 v51, 0xffff0000, v18
	v_mul_f32_e32 v50, 0xbfb8aa3b, v50
	v_mul_f32_e32 v51, 0xbfb8aa3b, v51
	v_exp_f32_e32 v50, v50
	v_exp_f32_e32 v51, v51
	v_and_b32_e32 v53, 0xffff0000, v42
	v_and_b32_e32 v52, 0xffff0000, v30
	v_add_f32_e32 v50, 1.0, v50
	v_add_f32_e32 v51, 1.0, v51
	v_rcp_f32_e32 v50, v50
	v_rcp_f32_e32 v51, v51
	s_nop 0
	v_pk_mul_f32 v[50:51], v[50:51], v[52:53]
	s_nop 0
	v_add_f32_e32 v50, v50, v51
	v_cvt_pk_bf16_f32 v50, v0, v50
	v_lshlrev_b32_e32 v0, 16, v7
	v_mul_f32_e32 v0, 0xbfb8aa3b, v0
	v_exp_f32_e32 v0, v0
	v_and_b32_e32 v51, 0xffff0000, v7
	v_mul_f32_e32 v51, 0xbfb8aa3b, v51
	v_exp_f32_e32 v51, v51
	v_add_f32_e32 v0, 1.0, v0
	v_rcp_f32_e32 v52, v0
	v_lshlrev_b32_e32 v0, 16, v19
	v_mul_f32_e32 v0, 0xbfb8aa3b, v0
	v_exp_f32_e32 v0, v0
	v_add_f32_e32 v51, 1.0, v51
	v_add_f32_e32 v0, 1.0, v0
	v_rcp_f32_e32 v53, v0
	s_nop 0
	v_pk_mul_f32 v[52:53], v[52:53], v[54:55]
	s_nop 0
	v_add_f32_e32 v0, v52, v53
	v_rcp_f32_e32 v52, v51
	v_and_b32_e32 v51, 0xffff0000, v19
	v_mul_f32_e32 v51, 0xbfb8aa3b, v51
	v_exp_f32_e32 v51, v51
	v_and_b32_e32 v55, 0xffff0000, v43
	v_and_b32_e32 v54, 0xffff0000, v31
	v_add_f32_e32 v51, 1.0, v51
	v_rcp_f32_e32 v53, v51
	s_nop 0
	v_pk_mul_f32 v[52:53], v[52:53], v[54:55]
	s_nop 0
	v_add_f32_e32 v51, v52, v53
	v_cvt_pk_bf16_f32 v51, v0, v51
	v_lshlrev_b32_e32 v0, 16, v8
	v_mul_f32_e32 v0, 0xbfb8aa3b, v0
	v_exp_f32_e32 v0, v0
	v_lshlrev_b32_e32 v55, 16, v44
	v_lshlrev_b32_e32 v54, 16, v32
	v_add_f32_e32 v0, 1.0, v0
	v_rcp_f32_e32 v52, v0
	v_lshlrev_b32_e32 v0, 16, v20
	v_mul_f32_e32 v0, 0xbfb8aa3b, v0
	v_exp_f32_e32 v0, v0
	s_nop 0
	v_add_f32_e32 v0, 1.0, v0
	v_rcp_f32_e32 v53, v0
	s_nop 0
	v_pk_mul_f32 v[52:53], v[52:53], v[54:55]
	s_nop 0
	v_add_f32_e32 v0, v52, v53
	v_and_b32_e32 v52, 0xffff0000, v8
	v_and_b32_e32 v53, 0xffff0000, v20
	v_mul_f32_e32 v52, 0xbfb8aa3b, v52
	v_mul_f32_e32 v53, 0xbfb8aa3b, v53
	v_exp_f32_e32 v52, v52
	v_exp_f32_e32 v53, v53
	v_and_b32_e32 v55, 0xffff0000, v44
	v_and_b32_e32 v54, 0xffff0000, v32
	v_add_f32_e32 v52, 1.0, v52
	v_add_f32_e32 v53, 1.0, v53
	v_rcp_f32_e32 v52, v52
	v_rcp_f32_e32 v53, v53
	s_nop 0
	v_pk_mul_f32 v[52:53], v[52:53], v[54:55]
	s_nop 0
	v_add_f32_e32 v52, v52, v53
	v_cvt_pk_bf16_f32 v52, v0, v52
	v_lshlrev_b32_e32 v0, 16, v9
	v_mul_f32_e32 v0, 0xbfb8aa3b, v0
	v_exp_f32_e32 v0, v0
	v_and_b32_e32 v53, 0xffff0000, v9
	v_mul_f32_e32 v53, 0xbfb8aa3b, v53
	v_exp_f32_e32 v53, v53
	v_add_f32_e32 v0, 1.0, v0
	v_rcp_f32_e32 v54, v0
	v_lshlrev_b32_e32 v0, 16, v21
	v_mul_f32_e32 v0, 0xbfb8aa3b, v0
	v_exp_f32_e32 v0, v0
	v_add_f32_e32 v53, 1.0, v53
	v_add_f32_e32 v0, 1.0, v0
	v_rcp_f32_e32 v55, v0
	s_nop 0
	v_pk_mul_f32 v[54:55], v[54:55], v[56:57]
	s_nop 0
	v_add_f32_e32 v0, v54, v55
	v_rcp_f32_e32 v54, v53
	v_and_b32_e32 v53, 0xffff0000, v21
	v_mul_f32_e32 v53, 0xbfb8aa3b, v53
	v_exp_f32_e32 v53, v53
	v_and_b32_e32 v57, 0xffff0000, v45
	v_and_b32_e32 v56, 0xffff0000, v33
	v_add_f32_e32 v53, 1.0, v53
	v_rcp_f32_e32 v55, v53
	s_nop 0
	v_pk_mul_f32 v[54:55], v[54:55], v[56:57]
	s_nop 0
	v_add_f32_e32 v53, v54, v55
	v_lshl_add_u64 v[54:55], v[80:81], 0, s[46:47]
	v_cvt_pk_bf16_f32 v53, v0, v53
	global_store_dwordx4 v[54:55], v[50:53], off sc1
	s_branch .LBB0_98

.LBB0_115:
	v_lshl_add_u64 v[14:15], s[62:63], 0, v[10:11]
	v_add_co_u32_e32 v2, vcc, 0xa200000, v14
	v_ashrrev_i64 v[18:19], 22, v[8:9]
	s_nop 0
	v_addc_co_u32_e32 v3, vcc, 0, v15, vcc
	global_load_dwordx4 v[2:5], v[2:3], off
	v_add_co_u32_e32 v14, vcc, 0xc280000, v14
	v_and_b32_e32 v0, 0x3f8, v12
	s_nop 0
	v_addc_co_u32_e32 v15, vcc, 0, v15, vcc
	global_load_dwordx4 v[14:17], v[14:15], off
	v_and_b32_e32 v18, 0xfffffc00, v18
	v_and_b32_e32 v19, 0x7fffffff, v19
	v_or_b32_e32 v18, v18, v0
	v_lshlrev_b64 v[46:47], 1, v[18:19]
	v_lshl_add_u64 v[18:19], s[44:45], 0, v[46:47]
	v_lshl_add_u64 v[22:23], s[22:23], 0, v[46:47]
	global_load_dwordx4 v[18:21], v[18:19], off
	v_lshl_add_u64 v[26:27], s[28:29], 0, v[46:47]
	global_load_dwordx4 v[22:25], v[22:23], off
	s_waitcnt lgkmcnt(0)
	v_lshl_add_u64 v[30:31], s[36:37], 0, v[46:47]
	global_load_dwordx4 v[26:29], v[26:27], off
	v_lshl_add_u64 v[34:35], s[38:39], 0, v[46:47]
	global_load_dwordx4 v[30:33], v[30:31], off
	v_lshl_add_u64 v[38:39], s[42:43], 0, v[46:47]
	global_load_dwordx4 v[34:37], v[34:35], off
	v_lshl_add_u64 v[42:43], s[46:47], 0, v[46:47]
	global_load_dwordx4 v[38:41], v[38:39], off
	v_lshl_add_u64 v[46:47], s[64:65], 0, v[46:47]
	global_load_dwordx4 v[42:45], v[42:43], off
	v_lshl_add_u64 v[6:7], v[6:7], 0, s[20:21]
	global_load_dwordx4 v[46:49], v[46:47], off
	s_mov_b64 s[2:3], 0x207fff
	v_cmp_lt_u64_e32 vcc, s[2:3], v[6:7]
	v_lshl_add_u64 v[8:9], v[8:9], 0, s[68:69]
	v_lshl_add_u64 v[12:13], v[12:13], 0, s[72:73]
	s_or_b64 s[30:31], vcc, s[30:31]
	s_waitcnt vmcnt(9)
	v_lshlrev_b32_e32 v0, 16, v2
	v_mul_f32_e32 v0, 0xbfb8aa3b, v0
	v_exp_f32_e32 v0, v0
	v_and_b32_e32 v2, 0xffff0000, v2
	v_mul_f32_e32 v2, 0xbfb8aa3b, v2
	v_exp_f32_e32 v2, v2
	v_add_f32_e32 v0, 1.0, v0
	v_rcp_f32_e32 v50, v0
	s_waitcnt vmcnt(8)
	v_lshlrev_b32_e32 v0, 16, v14
	v_mul_f32_e32 v0, 0xbfb8aa3b, v0
	v_exp_f32_e32 v0, v0
	v_add_f32_e32 v2, 1.0, v2
	s_waitcnt vmcnt(7)
	v_lshlrev_b32_e32 v52, 16, v18
	v_add_f32_e32 v0, 1.0, v0
	s_waitcnt vmcnt(6)
	v_lshlrev_b32_e32 v53, 16, v22
	v_rcp_f32_e32 v51, v0
	v_pk_add_f32 v[52:53], v[52:53], 0 op_sel_hi:[1,0]
	s_waitcnt vmcnt(5)
	v_lshlrev_b32_e32 v54, 16, v26
	s_waitcnt vmcnt(4)
	v_lshlrev_b32_e32 v55, 16, v30
	v_pk_add_f32 v[52:53], v[52:53], v[54:55]
	s_waitcnt vmcnt(3)
	v_lshlrev_b32_e32 v54, 16, v34
	s_waitcnt vmcnt(2)
	v_lshlrev_b32_e32 v55, 16, v38
	v_pk_add_f32 v[52:53], v[52:53], v[54:55]
	s_waitcnt vmcnt(1)
	v_lshlrev_b32_e32 v54, 16, v42
	s_waitcnt vmcnt(0)
	v_lshlrev_b32_e32 v55, 16, v46
	v_pk_add_f32 v[52:53], v[52:53], v[54:55]
	v_and_b32_e32 v55, 0xffff0000, v30
	v_pk_mul_f32 v[50:51], v[50:51], v[52:53]
	v_and_b32_e32 v53, 0xffff0000, v22
	v_add_f32_e32 v0, v50, v51
	v_rcp_f32_e32 v50, v2
	v_and_b32_e32 v2, 0xffff0000, v14
	v_mul_f32_e32 v2, 0xbfb8aa3b, v2
	v_exp_f32_e32 v2, v2
	v_and_b32_e32 v52, 0xffff0000, v18
	v_pk_add_f32 v[52:53], v[52:53], 0 op_sel_hi:[1,0]
	v_and_b32_e32 v54, 0xffff0000, v26
	v_add_f32_e32 v2, 1.0, v2
	v_rcp_f32_e32 v51, v2
	v_pk_add_f32 v[52:53], v[52:53], v[54:55]
	v_and_b32_e32 v55, 0xffff0000, v38
	v_and_b32_e32 v54, 0xffff0000, v34
	v_pk_add_f32 v[52:53], v[52:53], v[54:55]
	v_and_b32_e32 v55, 0xffff0000, v46
	v_and_b32_e32 v54, 0xffff0000, v42
	v_pk_add_f32 v[52:53], v[52:53], v[54:55]
	v_and_b32_e32 v22, 0xffff0000, v19
	v_pk_mul_f32 v[50:51], v[50:51], v[52:53]
	v_lshlrev_b32_e32 v53, 16, v23
	v_add_f32_e32 v2, v50, v51
	v_cvt_pk_bf16_f32 v2, v0, v2
	v_lshlrev_b32_e32 v0, 16, v3
	v_and_b32_e32 v3, 0xffff0000, v3
	v_mul_f32_e32 v0, 0xbfb8aa3b, v0
	v_mul_f32_e32 v3, 0xbfb8aa3b, v3
	v_exp_f32_e32 v0, v0
	v_exp_f32_e32 v3, v3
	v_lshlrev_b32_e32 v52, 16, v19
	v_and_b32_e32 v23, 0xffff0000, v23
	v_add_f32_e32 v0, 1.0, v0
	v_add_f32_e32 v3, 1.0, v3
	v_rcp_f32_e32 v50, v0
	v_lshlrev_b32_e32 v0, 16, v15
	v_rcp_f32_e32 v14, v3
	v_and_b32_e32 v3, 0xffff0000, v15
	v_mul_f32_e32 v0, 0xbfb8aa3b, v0
	v_mul_f32_e32 v3, 0xbfb8aa3b, v3
	v_exp_f32_e32 v0, v0
	v_exp_f32_e32 v3, v3
	v_pk_add_f32 v[52:53], v[52:53], 0 op_sel_hi:[1,0]
	v_lshlrev_b32_e32 v55, 16, v31
	v_add_f32_e32 v0, 1.0, v0
	v_add_f32_e32 v3, 1.0, v3
	v_rcp_f32_e32 v51, v0
	v_lshlrev_b32_e32 v54, 16, v27
	v_rcp_f32_e32 v15, v3
	v_pk_add_f32 v[18:19], v[22:23], 0 op_sel_hi:[1,0]
	v_and_b32_e32 v23, 0xffff0000, v31
	v_and_b32_e32 v22, 0xffff0000, v27
	v_pk_add_f32 v[52:53], v[52:53], v[54:55]
	v_lshlrev_b32_e32 v55, 16, v39
	v_lshlrev_b32_e32 v54, 16, v35
	v_pk_add_f32 v[18:19], v[18:19], v[22:23]
	v_and_b32_e32 v23, 0xffff0000, v39
	v_and_b32_e32 v22, 0xffff0000, v35
	v_pk_add_f32 v[52:53], v[52:53], v[54:55]
	v_lshlrev_b32_e32 v55, 16, v47
	v_lshlrev_b32_e32 v54, 16, v43
	v_pk_add_f32 v[18:19], v[18:19], v[22:23]
	v_and_b32_e32 v23, 0xffff0000, v47
	v_and_b32_e32 v22, 0xffff0000, v43
	v_pk_add_f32 v[52:53], v[52:53], v[54:55]
	v_pk_add_f32 v[18:19], v[18:19], v[22:23]
	v_pk_mul_f32 v[50:51], v[50:51], v[52:53]
	v_pk_mul_f32 v[14:15], v[14:15], v[18:19]
	v_add_f32_e32 v0, v50, v51
	v_add_f32_e32 v3, v14, v15
	v_cvt_pk_bf16_f32 v3, v0, v3
	v_lshlrev_b32_e32 v0, 16, v4
	v_mul_f32_e32 v0, 0xbfb8aa3b, v0
	v_exp_f32_e32 v0, v0
	v_and_b32_e32 v4, 0xffff0000, v4
	v_lshlrev_b32_e32 v19, 16, v24
	v_lshlrev_b32_e32 v18, 16, v20
	v_add_f32_e32 v0, 1.0, v0
	v_rcp_f32_e32 v14, v0
	v_lshlrev_b32_e32 v0, 16, v16
	v_mul_f32_e32 v0, 0xbfb8aa3b, v0
	v_exp_f32_e32 v0, v0
	v_mul_f32_e32 v4, 0xbfb8aa3b, v4
	v_pk_add_f32 v[18:19], v[18:19], 0 op_sel_hi:[1,0]
	v_lshlrev_b32_e32 v23, 16, v32
	v_add_f32_e32 v0, 1.0, v0
	v_rcp_f32_e32 v15, v0
	v_lshlrev_b32_e32 v22, 16, v28
	v_exp_f32_e32 v4, v4
	v_pk_add_f32 v[18:19], v[18:19], v[22:23]
	v_lshlrev_b32_e32 v23, 16, v40
	v_lshlrev_b32_e32 v22, 16, v36
	v_pk_add_f32 v[18:19], v[18:19], v[22:23]
	v_lshlrev_b32_e32 v23, 16, v48
	v_lshlrev_b32_e32 v22, 16, v44
	v_pk_add_f32 v[18:19], v[18:19], v[22:23]
	v_add_f32_e32 v4, 1.0, v4
	v_pk_mul_f32 v[14:15], v[14:15], v[18:19]
	v_and_b32_e32 v19, 0xffff0000, v24
	v_add_f32_e32 v0, v14, v15
	v_rcp_f32_e32 v14, v4
	v_and_b32_e32 v4, 0xffff0000, v16
	v_mul_f32_e32 v4, 0xbfb8aa3b, v4
	v_exp_f32_e32 v4, v4
	v_and_b32_e32 v18, 0xffff0000, v20
	v_pk_add_f32 v[18:19], v[18:19], 0 op_sel_hi:[1,0]
	v_and_b32_e32 v23, 0xffff0000, v32
	v_add_f32_e32 v4, 1.0, v4
	v_rcp_f32_e32 v15, v4
	v_and_b32_e32 v22, 0xffff0000, v28
	v_pk_add_f32 v[18:19], v[18:19], v[22:23]
	v_and_b32_e32 v23, 0xffff0000, v40
	v_and_b32_e32 v22, 0xffff0000, v36
	v_pk_add_f32 v[18:19], v[18:19], v[22:23]
	v_and_b32_e32 v23, 0xffff0000, v48
	v_and_b32_e32 v22, 0xffff0000, v44
	v_pk_add_f32 v[18:19], v[18:19], v[22:23]
	v_lshlrev_b32_e32 v23, 16, v33
	v_pk_mul_f32 v[14:15], v[14:15], v[18:19]
	v_lshlrev_b32_e32 v19, 16, v25
	v_add_f32_e32 v4, v14, v15
	v_cvt_pk_bf16_f32 v4, v0, v4
	v_lshlrev_b32_e32 v0, 16, v5
	v_mul_f32_e32 v0, 0xbfb8aa3b, v0
	v_exp_f32_e32 v0, v0
	v_and_b32_e32 v5, 0xffff0000, v5
	v_lshlrev_b32_e32 v18, 16, v21
	v_mul_f32_e32 v5, 0xbfb8aa3b, v5
	v_add_f32_e32 v0, 1.0, v0
	v_rcp_f32_e32 v14, v0
	v_lshlrev_b32_e32 v0, 16, v17
	v_mul_f32_e32 v0, 0xbfb8aa3b, v0
	v_exp_f32_e32 v0, v0
	v_pk_add_f32 v[18:19], v[18:19], 0 op_sel_hi:[1,0]
	v_lshlrev_b32_e32 v22, 16, v29
	v_exp_f32_e32 v5, v5
	v_add_f32_e32 v0, 1.0, v0
	v_rcp_f32_e32 v15, v0
	v_pk_add_f32 v[18:19], v[18:19], v[22:23]
	v_lshlrev_b32_e32 v23, 16, v41
	v_lshlrev_b32_e32 v22, 16, v37
	v_pk_add_f32 v[18:19], v[18:19], v[22:23]
	v_lshlrev_b32_e32 v23, 16, v49
	v_lshlrev_b32_e32 v22, 16, v45
	v_pk_add_f32 v[18:19], v[18:19], v[22:23]
	v_add_f32_e32 v5, 1.0, v5
	v_pk_mul_f32 v[14:15], v[14:15], v[18:19]
	v_and_b32_e32 v16, 0xffff0000, v21
	v_add_f32_e32 v0, v14, v15
	v_rcp_f32_e32 v14, v5
	v_and_b32_e32 v5, 0xffff0000, v17
	v_mul_f32_e32 v5, 0xbfb8aa3b, v5
	v_exp_f32_e32 v5, v5
	v_and_b32_e32 v17, 0xffff0000, v25
	v_pk_add_f32 v[16:17], v[16:17], 0 op_sel_hi:[1,0]
	v_and_b32_e32 v19, 0xffff0000, v33
	v_add_f32_e32 v5, 1.0, v5
	v_rcp_f32_e32 v15, v5
	v_and_b32_e32 v18, 0xffff0000, v29
	v_pk_add_f32 v[16:17], v[16:17], v[18:19]
	v_and_b32_e32 v19, 0xffff0000, v41
	v_and_b32_e32 v18, 0xffff0000, v37
	v_pk_add_f32 v[16:17], v[16:17], v[18:19]
	v_and_b32_e32 v19, 0xffff0000, v49
	v_and_b32_e32 v18, 0xffff0000, v45
	v_pk_add_f32 v[16:17], v[16:17], v[18:19]
	s_nop 0
	v_pk_mul_f32 v[14:15], v[14:15], v[16:17]
	s_nop 0
	v_add_f32_e32 v5, v14, v15
	v_lshl_add_u64 v[14:15], s[70:71], 0, v[10:11]
	v_lshl_add_u64 v[10:11], v[10:11], 0, s[66:67]
	v_cvt_pk_bf16_f32 v5, v0, v5
	global_store_dwordx4 v[14:15], v[2:5], off sc1
	s_andn2_b64 exec, exec, s[30:31]
	s_cbranch_execnz .LBB0_115

.LBB0_173:
	s_add_i32 s33, s23, 1
	s_cmp_eq_u32 s33, 42
	s_cselect_b64 s[30:31], -1, 0
	s_lshl_b64 s[2:3], s[0:1], 12
	s_add_u32 s1, s60, s2
	s_addc_u32 s3, s61, s3
	s_add_u32 s2, s1, 0x40a8000
	s_mul_hi_i32 s21, s0, 0xac00
	s_mul_i32 s20, s0, 0xac00
	s_addc_u32 s3, s3, 0
	s_and_b64 vcc, exec, s[30:31]
	ds_write_b32 v0, v46
	s_cbranch_vccz .LBB0_175
	v_readlane_b32 s36, v251, 11
	v_lshl_add_u64 v[10:11], s[20:21], 0, v[142:143]
	v_readlane_b32 s37, v251, 12
	v_lshl_add_u64 v[12:13], v[142:143], 2, s[2:3]
	s_nop 0
	v_lshl_add_u64 v[10:11], v[10:11], 3, s[36:37]
	v_add_co_u32_e32 v10, vcc, 0x54000, v10
	s_nop 1
	v_addc_co_u32_e32 v11, vcc, 0, v11, vcc
	global_load_dwordx2 v[10:11], v[10:11], off
	s_waitcnt vmcnt(0)
	v_fmac_f32_e32 v11, v46, v10
	global_store_dword v[12:13], v11, off sc1

.LBB0_208:
	s_andn2_b64 vcc, exec, s[30:31]
	ds_write_b32 v0, v46 offset:2048
	s_cbranch_vccnz .LBB0_210
	v_lshl_add_u64 v[10:11], s[20:21], 0, v[4:5]
	v_readlane_b32 s20, v251, 11
	v_readlane_b32 s21, v251, 12
	v_lshl_add_u64 v[12:13], v[4:5], 2, s[2:3]
	s_nop 0
	v_lshl_add_u64 v[10:11], v[10:11], 3, s[20:21]
	v_add_co_u32_e32 v10, vcc, 0x54000, v10
	s_nop 1
	v_addc_co_u32_e32 v11, vcc, 0, v11, vcc
	global_load_dwordx2 v[10:11], v[10:11], off
	s_waitcnt vmcnt(0)
	v_fmac_f32_e32 v11, v46, v10
	global_store_dword v[12:13], v11, off sc1

.LBB0_211:
	s_nop 0
	v_ashrrev_i32_e32 v12, 7, v10
	v_ashrrev_i32_e32 v13, 31, v12
	v_lshl_add_u64 v[12:13], s[0:1], 0, v[12:13]
	v_lshlrev_b64 v[54:55], 11, v[12:13]
	v_or_b32_e32 v16, v54, v45
	v_mov_b32_e32 v17, v55
	v_lshl_add_u64 v[12:13], s[20:21], 0, v[16:17]
	v_lshl_add_u64 v[16:17], s[60:61], 0, v[16:17]
	global_load_dwordx4 v[12:15], v[12:13], off
	v_add_u32_e32 v11, 0x200, v10
	global_load_dwordx4 v[16:19], v[16:17], off nt
	v_ashrrev_i32_e32 v20, 7, v11
	v_ashrrev_i32_e32 v21, 31, v20
	v_lshl_add_u64 v[20:21], s[0:1], 0, v[20:21]
	v_lshlrev_b64 v[56:57], 11, v[20:21]
	v_or_b32_e32 v24, v56, v45
	v_mov_b32_e32 v25, v57
	v_lshl_add_u64 v[20:21], s[20:21], 0, v[24:25]
	v_lshl_add_u64 v[24:25], s[60:61], 0, v[24:25]
	global_load_dwordx4 v[20:23], v[20:21], off
	v_add_u32_e32 v11, 0x400, v10
	global_load_dwordx4 v[24:27], v[24:25], off nt
	v_ashrrev_i32_e32 v28, 7, v11
	v_ashrrev_i32_e32 v29, 31, v28
	v_lshl_add_u64 v[28:29], s[0:1], 0, v[28:29]
	v_lshlrev_b64 v[58:59], 11, v[28:29]
	v_or_b32_e32 v32, v58, v45
	v_mov_b32_e32 v33, v59
	v_lshl_add_u64 v[28:29], s[20:21], 0, v[32:33]
	v_lshl_add_u64 v[32:33], s[60:61], 0, v[32:33]
	global_load_dwordx4 v[28:31], v[28:29], off
	v_add_u32_e32 v11, 0x600, v10
	global_load_dwordx4 v[32:35], v[32:33], off nt
	v_ashrrev_i32_e32 v36, 7, v11
	v_ashrrev_i32_e32 v37, 31, v36
	v_lshl_add_u64 v[36:37], s[0:1], 0, v[36:37]
	v_lshlrev_b64 v[60:61], 11, v[36:37]
	v_or_b32_e32 v40, v60, v45
	v_mov_b32_e32 v41, v61
	v_lshl_add_u64 v[36:37], s[20:21], 0, v[40:41]
	v_lshl_add_u64 v[40:41], s[60:61], 0, v[40:41]
	global_load_dwordx4 v[36:39], v[36:37], off
	s_add_i32 s2, s2, 4
	global_load_dwordx4 v[40:43], v[40:41], off nt
	ds_read_b128 v[46:49], v44
	ds_read_b128 v[50:53], v44 offset:16
	v_add_u32_e32 v10, 0x800, v10
	s_cmp_lt_u32 s2, 8
	s_waitcnt vmcnt(7)
	v_lshlrev_b32_e32 v11, 16, v12
	v_and_b32_e32 v12, 0xffff0000, v12
	s_waitcnt vmcnt(6)
	v_lshlrev_b32_e32 v62, 16, v16
	v_and_b32_e32 v16, 0xffff0000, v16
	s_waitcnt lgkmcnt(1)
	v_fmac_f32_e32 v11, v46, v62
	v_fmac_f32_e32 v12, v47, v16
	v_cvt_pk_bf16_f32 v12, v11, v12
	v_lshlrev_b32_e32 v11, 16, v13
	v_lshlrev_b32_e32 v16, 16, v17
	v_fmac_f32_e32 v11, v48, v16
	v_and_b32_e32 v13, 0xffff0000, v13
	v_and_b32_e32 v16, 0xffff0000, v17
	v_fmac_f32_e32 v13, v49, v16
	v_cvt_pk_bf16_f32 v13, v11, v13
	v_lshlrev_b32_e32 v11, 16, v14
	v_lshlrev_b32_e32 v16, 16, v18
	s_waitcnt lgkmcnt(0)
	v_fmac_f32_e32 v11, v50, v16
	v_and_b32_e32 v14, 0xffff0000, v14
	v_and_b32_e32 v16, 0xffff0000, v18
	v_fmac_f32_e32 v14, v51, v16
	v_cvt_pk_bf16_f32 v14, v11, v14
	v_lshlrev_b32_e32 v11, 16, v15
	v_lshlrev_b32_e32 v16, 16, v19
	v_fmac_f32_e32 v11, v52, v16
	v_and_b32_e32 v15, 0xffff0000, v15
	v_and_b32_e32 v16, 0xffff0000, v19
	v_fmac_f32_e32 v15, v53, v16
	v_lshl_add_u64 v[16:17], v[2:3], 0, v[54:55]
	v_cvt_pk_bf16_f32 v15, v11, v15
	global_store_dwordx4 v[16:17], v[12:15], off sc1
	ds_read_b128 v[12:15], v44
	ds_read_b128 v[16:19], v44 offset:16
	s_waitcnt vmcnt(6)
	v_lshlrev_b32_e32 v11, 16, v20
	s_waitcnt vmcnt(5)
	v_lshlrev_b32_e32 v46, 16, v24
	s_waitcnt lgkmcnt(1)
	v_fmac_f32_e32 v11, v12, v46
	v_and_b32_e32 v12, 0xffff0000, v20
	v_and_b32_e32 v20, 0xffff0000, v24
	v_fmac_f32_e32 v12, v13, v20
	v_cvt_pk_bf16_f32 v12, v11, v12
	v_lshlrev_b32_e32 v11, 16, v21
	v_lshlrev_b32_e32 v13, 16, v25
	v_fmac_f32_e32 v11, v14, v13
	v_and_b32_e32 v13, 0xffff0000, v21
	v_and_b32_e32 v14, 0xffff0000, v25
	v_fmac_f32_e32 v13, v15, v14
	v_cvt_pk_bf16_f32 v13, v11, v13
	v_lshlrev_b32_e32 v11, 16, v22
	v_lshlrev_b32_e32 v14, 16, v26
	s_waitcnt lgkmcnt(0)
	v_fmac_f32_e32 v11, v16, v14
	v_and_b32_e32 v14, 0xffff0000, v22
	v_and_b32_e32 v15, 0xffff0000, v26
	v_fmac_f32_e32 v14, v17, v15
	v_cvt_pk_bf16_f32 v14, v11, v14
	v_lshlrev_b32_e32 v11, 16, v23
	v_lshlrev_b32_e32 v15, 16, v27
	v_fmac_f32_e32 v11, v18, v15
	v_and_b32_e32 v15, 0xffff0000, v23
	v_and_b32_e32 v16, 0xffff0000, v27
	v_fmac_f32_e32 v15, v19, v16
	v_lshl_add_u64 v[16:17], v[2:3], 0, v[56:57]
	v_cvt_pk_bf16_f32 v15, v11, v15
	global_store_dwordx4 v[16:17], v[12:15], off sc1
	ds_read_b128 v[12:15], v44
	ds_read_b128 v[16:19], v44 offset:16
	s_waitcnt vmcnt(5)
	v_lshlrev_b32_e32 v11, 16, v28
	s_waitcnt vmcnt(4)
	v_lshlrev_b32_e32 v20, 16, v32
	s_waitcnt lgkmcnt(1)
	v_fmac_f32_e32 v11, v12, v20
	v_and_b32_e32 v12, 0xffff0000, v28
	v_and_b32_e32 v20, 0xffff0000, v32
	v_fmac_f32_e32 v12, v13, v20
	v_cvt_pk_bf16_f32 v12, v11, v12
	v_lshlrev_b32_e32 v11, 16, v29
	v_lshlrev_b32_e32 v13, 16, v33
	v_fmac_f32_e32 v11, v14, v13
	v_and_b32_e32 v13, 0xffff0000, v29
	v_and_b32_e32 v14, 0xffff0000, v33
	v_fmac_f32_e32 v13, v15, v14
	v_cvt_pk_bf16_f32 v13, v11, v13
	v_lshlrev_b32_e32 v11, 16, v30
	v_lshlrev_b32_e32 v14, 16, v34
	s_waitcnt lgkmcnt(0)
	v_fmac_f32_e32 v11, v16, v14
	v_and_b32_e32 v14, 0xffff0000, v30
	v_and_b32_e32 v15, 0xffff0000, v34
	v_fmac_f32_e32 v14, v17, v15
	v_cvt_pk_bf16_f32 v14, v11, v14
	v_lshlrev_b32_e32 v11, 16, v31
	v_lshlrev_b32_e32 v15, 16, v35
	v_fmac_f32_e32 v11, v18, v15
	v_and_b32_e32 v15, 0xffff0000, v31
	v_and_b32_e32 v16, 0xffff0000, v35
	v_fmac_f32_e32 v15, v19, v16
	v_lshl_add_u64 v[16:17], v[2:3], 0, v[58:59]
	v_cvt_pk_bf16_f32 v15, v11, v15
	global_store_dwordx4 v[16:17], v[12:15], off sc1
	ds_read_b128 v[12:15], v44
	ds_read_b128 v[16:19], v44 offset:16
	s_waitcnt vmcnt(4)
	v_lshlrev_b32_e32 v11, 16, v36
	s_waitcnt vmcnt(3)
	v_lshlrev_b32_e32 v20, 16, v40
	s_waitcnt lgkmcnt(1)
	v_fmac_f32_e32 v11, v12, v20
	v_and_b32_e32 v12, 0xffff0000, v36
	v_and_b32_e32 v20, 0xffff0000, v40
	v_fmac_f32_e32 v12, v13, v20
	v_cvt_pk_bf16_f32 v12, v11, v12
	v_lshlrev_b32_e32 v11, 16, v37
	v_lshlrev_b32_e32 v13, 16, v41
	v_fmac_f32_e32 v11, v14, v13
	v_and_b32_e32 v13, 0xffff0000, v37
	v_and_b32_e32 v14, 0xffff0000, v41
	v_fmac_f32_e32 v13, v15, v14
	v_cvt_pk_bf16_f32 v13, v11, v13
	v_lshlrev_b32_e32 v11, 16, v38
	v_lshlrev_b32_e32 v14, 16, v42
	s_waitcnt lgkmcnt(0)
	v_fmac_f32_e32 v11, v16, v14
	v_and_b32_e32 v14, 0xffff0000, v38
	v_and_b32_e32 v15, 0xffff0000, v42
	v_fmac_f32_e32 v14, v17, v15
	v_cvt_pk_bf16_f32 v14, v11, v14
	v_lshlrev_b32_e32 v11, 16, v39
	v_lshlrev_b32_e32 v15, 16, v43
	v_fmac_f32_e32 v11, v18, v15
	v_and_b32_e32 v15, 0xffff0000, v39
	v_and_b32_e32 v16, 0xffff0000, v43
	v_fmac_f32_e32 v15, v19, v16
	v_lshl_add_u64 v[16:17], v[2:3], 0, v[60:61]
	v_cvt_pk_bf16_f32 v15, v11, v15
	global_store_dwordx4 v[16:17], v[12:15], off sc1
	s_cbranch_scc1 .LBB0_211
	s_add_i32 s22, s22, s24
	s_cmpk_lt_i32 s22, 0x150
	s_barrier
	s_cbranch_scc1 .LBB0_140

.LBB0_219:
	s_movk_i32 s3, 0xf000
	v_add_co_u32_e32 v88, vcc, s3, v78
	s_mov_b32 s3, 0xfbeff000
	s_nop 0
	v_addc_co_u32_e32 v89, vcc, -1, v79, vcc
	v_add_co_u32_e32 v126, vcc, s3, v78
	global_load_dwordx4 v[94:97], v[88:89], off offset:-2048 nt
	s_nop 0
	v_addc_co_u32_e32 v127, vcc, -1, v79, vcc
	global_load_dwordx4 v[98:101], v[126:127], off offset:-2048
	global_load_dwordx4 v[102:105], v[78:79], off offset:-4096 nt
	s_mov_b32 s3, 0xfbf00000
	v_add_co_u32_e32 v88, vcc, s3, v78
	s_add_i32 s2, s2, 4
	s_nop 0
	v_addc_co_u32_e32 v89, vcc, -1, v79, vcc
	global_load_dwordx4 v[106:109], v[88:89], off offset:-4096
	global_load_dwordx4 v[110:113], v[78:79], off offset:-2048 nt
	global_load_dwordx4 v[114:117], v[88:89], off offset:-2048
	global_load_dwordx4 v[118:121], v[78:79], off nt
	global_load_dwordx4 v[122:125], v[88:89], off
	v_lshl_add_u64 v[78:79], v[78:79], 0, s[20:21]
	s_cmp_gt_u32 s2, 11
	s_waitcnt vmcnt(0)
	v_lshlrev_b32_e32 v29, 16, v98
	v_and_b32_e32 v33, 0xffff0000, v98
	v_lshlrev_b32_e32 v98, 16, v94
	v_mov_b32_e32 v27, v98
	v_lshlrev_b32_e32 v35, 16, v99
	v_and_b32_e32 v37, 0xffff0000, v99
	v_lshlrev_b32_e32 v39, 16, v100
	v_and_b32_e32 v41, 0xffff0000, v100
	v_lshlrev_b32_e32 v43, 16, v101
	v_and_b32_e32 v45, 0xffff0000, v101
	s_waitcnt vmcnt(5)
	v_lshlrev_b32_e32 v99, 16, v102
	v_pk_mul_f32 v[100:101], v[60:61], v[26:27]
	s_waitcnt vmcnt(4)
	v_lshlrev_b32_e32 v47, 16, v106
	v_fma_f32 v27, v6, v30, v100
	s_waitcnt lgkmcnt(0)
	v_pk_mul_f32 v[30:31], v[60:61], v[98:99]
	v_and_b32_e32 v100, 0xffff0000, v94
	v_fma_f32 v26, v6, v26, v30
	v_add_f32_e32 v27, v27, v101
	v_add_f32_e32 v26, v26, v31
	v_mov_b32_e32 v87, v100
	v_mul_f32_e32 v29, v27, v29
	v_mul_f32_e32 v47, v26, v47
	v_pk_mul_f32 v[26:27], v[14:15], v[86:87]
	v_and_b32_e32 v101, 0xffff0000, v102
	v_fma_f32 v26, v7, v44, v26
	v_add_f32_e32 v26, v26, v27
	v_pk_mul_f32 v[30:31], v[14:15], v[100:101]
	v_mul_f32_e32 v26, v26, v33
	v_fma_f32 v27, v7, v86, v30
	v_lshlrev_b32_e32 v86, 16, v95
	v_cvt_pk_bf16_f32 v26, v29, v26
	v_mov_b32_e32 v29, v86
	v_and_b32_e32 v49, 0xffff0000, v106
	v_add_f32_e32 v27, v27, v31
	v_pk_mul_f32 v[30:31], v[58:59], v[28:29]
	v_mul_f32_e32 v33, v27, v49
	v_lshlrev_b32_e32 v87, 16, v103
	v_fma_f32 v27, v8, v32, v30
	v_add_f32_e32 v27, v27, v31
	v_pk_mul_f32 v[30:31], v[58:59], v[86:87]
	v_and_b32_e32 v102, 0xffff0000, v95
	v_fma_f32 v28, v8, v28, v30
	v_lshlrev_b32_e32 v51, 16, v107
	v_add_f32_e32 v28, v28, v31
	v_mov_b32_e32 v85, v102
	v_mul_f32_e32 v32, v28, v51
	v_pk_mul_f32 v[28:29], v[16:17], v[84:85]
	v_mul_f32_e32 v27, v27, v35
	v_fma_f32 v28, v9, v48, v28
	v_add_f32_e32 v28, v28, v29
	v_and_b32_e32 v103, 0xffff0000, v103
	v_mul_f32_e32 v28, v28, v37
	v_cvt_pk_bf16_f32 v27, v27, v28
	v_pk_mul_f32 v[28:29], v[16:17], v[102:103]
	v_and_b32_e32 v53, 0xffff0000, v107
	v_fma_f32 v28, v9, v84, v28
	v_lshlrev_b32_e32 v84, 16, v96
	v_add_f32_e32 v28, v28, v29
	v_mov_b32_e32 v35, v84
	v_mul_f32_e32 v44, v28, v53
	v_pk_mul_f32 v[28:29], v[56:57], v[34:35]
	v_lshlrev_b32_e32 v85, 16, v104
	v_fma_f32 v28, v2, v38, v28
	v_add_f32_e32 v28, v28, v29
	v_mul_f32_e32 v30, v28, v39
	v_pk_mul_f32 v[28:29], v[56:57], v[84:85]
	v_and_b32_e32 v94, 0xffff0000, v96
	v_fma_f32 v28, v2, v34, v28
	v_lshlrev_b32_e32 v81, 16, v108
	v_add_f32_e32 v28, v28, v29
	v_mov_b32_e32 v83, v94
	v_mul_f32_e32 v34, v28, v81
	v_pk_mul_f32 v[28:29], v[22:23], v[82:83]
	v_and_b32_e32 v95, 0xffff0000, v104
	v_fma_f32 v28, v3, v46, v28
	v_add_f32_e32 v28, v28, v29
	v_mul_f32_e32 v28, v28, v41
	v_cvt_pk_bf16_f32 v28, v30, v28
	v_pk_mul_f32 v[30:31], v[22:23], v[94:95]
	v_and_b32_e32 v106, 0xffff0000, v108
	v_fma_f32 v29, v3, v82, v30
	v_add_f32_e32 v29, v29, v31
	v_mul_f32_e32 v35, v29, v106
	v_lshlrev_b32_e32 v106, 16, v97
	v_mov_b32_e32 v37, v106
	v_pk_mul_f32 v[30:31], v[54:55], v[36:37]
	v_lshlrev_b32_e32 v107, 16, v105
	v_fma_f32 v29, v4, v40, v30
	v_add_f32_e32 v29, v29, v31
	v_pk_mul_f32 v[30:31], v[54:55], v[106:107]
	v_and_b32_e32 v104, 0xffff0000, v97
	v_fma_f32 v30, v4, v36, v30
	v_lshlrev_b32_e32 v108, 16, v109
	v_add_f32_e32 v30, v30, v31
	v_mov_b32_e32 v81, v104
	v_mul_f32_e32 v36, v30, v108
	v_pk_mul_f32 v[30:31], v[24:25], v[80:81]
	v_mul_f32_e32 v29, v29, v43
	v_fma_f32 v30, v5, v50, v30
	v_and_b32_e32 v105, 0xffff0000, v105
	v_add_f32_e32 v30, v30, v31
	v_mul_f32_e32 v30, v30, v45
	v_cvt_pk_bf16_f32 v29, v29, v30
	global_store_dwordx4 v[126:127], v[26:29], off offset:-2048 sc1
	v_and_b32_e32 v109, 0xffff0000, v109
	s_waitcnt vmcnt(4)
	v_lshlrev_b32_e32 v30, 16, v110
	v_pk_mul_f32 v[26:27], v[24:25], v[104:105]
	s_waitcnt vmcnt(2)
	v_and_b32_e32 v45, 0xffff0000, v118
	v_fma_f32 v26, v5, v80, v26
	v_add_f32_e32 v26, v26, v27
	v_mul_f32_e32 v29, v26, v109
	v_cvt_pk_bf16_f32 v26, v47, v33
	v_cvt_pk_bf16_f32 v27, v32, v44
	v_cvt_pk_bf16_f32 v28, v34, v35
	v_cvt_pk_bf16_f32 v29, v36, v29
	global_store_dwordx4 v[88:89], v[26:29], off offset:-4096 sc1
	s_waitcnt vmcnt(2)
	v_lshlrev_b32_e32 v33, 16, v122
	v_and_b32_e32 v44, 0xffff0000, v110
	v_mov_b32_e32 v28, v98
	v_mov_b32_e32 v29, v30
	v_pk_mul_f32 v[28:29], v[74:75], v[28:29]
	v_lshlrev_b32_e32 v26, 16, v118
	v_fma_f32 v28, v10, v99, v28
	v_lshlrev_b32_e32 v27, 16, v114
	v_mov_b32_e32 v31, v26
	v_add_f32_e32 v28, v28, v29
	v_mul_f32_e32 v27, v28, v27
	v_pk_mul_f32 v[28:29], v[60:61], v[30:31]
	v_and_b32_e32 v32, 0xffff0000, v114
	v_fma_f32 v28, v6, v99, v28
	v_add_f32_e32 v28, v28, v29
	v_mul_f32_e32 v31, v28, v33
	v_mov_b32_e32 v28, v100
	v_mov_b32_e32 v29, v44
	v_pk_mul_f32 v[28:29], v[76:77], v[28:29]
	v_and_b32_e32 v34, 0xffff0000, v122
	v_fma_f32 v28, v11, v101, v28
	v_add_f32_e32 v28, v28, v29
	v_mul_f32_e32 v28, v28, v32
	v_cvt_pk_bf16_f32 v80, v27, v28
	v_pk_mul_f32 v[28:29], v[14:15], v[44:45]
	v_lshlrev_b32_e32 v32, 16, v111
	v_fma_f32 v27, v7, v101, v28
	v_add_f32_e32 v27, v27, v29
	v_mul_f32_e32 v27, v27, v34
	v_mov_b32_e32 v34, v86
	v_mov_b32_e32 v35, v32
	v_lshlrev_b32_e32 v28, 16, v119
	v_pk_mul_f32 v[34:35], v[70:71], v[34:35]
	v_mov_b32_e32 v33, v28
	v_fma_f32 v29, v12, v87, v34
	v_add_f32_e32 v29, v29, v35
	v_pk_mul_f32 v[34:35], v[58:59], v[32:33]
	v_and_b32_e32 v48, 0xffff0000, v111
	v_fma_f32 v33, v8, v87, v34
	v_add_f32_e32 v33, v33, v35
	v_mov_b32_e32 v34, v102
	v_mov_b32_e32 v35, v48
	v_pk_mul_f32 v[34:35], v[72:73], v[34:35]
	v_and_b32_e32 v37, 0xffff0000, v115
	v_fma_f32 v34, v13, v103, v34
	v_add_f32_e32 v34, v34, v35
	v_lshlrev_b32_e32 v36, 16, v115
	v_lshlrev_b32_e32 v38, 16, v123
	v_and_b32_e32 v49, 0xffff0000, v119
	v_mul_f32_e32 v34, v34, v37
	v_mul_f32_e32 v29, v29, v36
	v_mul_f32_e32 v33, v33, v38
	v_cvt_pk_bf16_f32 v81, v29, v34
	v_pk_mul_f32 v[34:35], v[16:17], v[48:49]
	v_lshlrev_b32_e32 v38, 16, v112
	v_fma_f32 v29, v9, v103, v34
	v_mov_b32_e32 v36, v84
	v_mov_b32_e32 v37, v38
	v_and_b32_e32 v39, 0xffff0000, v123
	v_add_f32_e32 v29, v29, v35
	v_lshlrev_b32_e32 v34, 16, v120
	v_pk_mul_f32 v[36:37], v[66:67], v[36:37]
	v_mul_f32_e32 v29, v29, v39
	v_mov_b32_e32 v39, v34
	v_fma_f32 v35, v18, v85, v36
	v_add_f32_e32 v35, v35, v37
	v_pk_mul_f32 v[36:37], v[56:57], v[38:39]
	v_lshlrev_b32_e32 v46, 16, v124
	v_fma_f32 v36, v2, v85, v36
	v_add_f32_e32 v36, v36, v37
	v_mul_f32_e32 v39, v36, v46
	v_and_b32_e32 v46, 0xffff0000, v112
	v_mov_b32_e32 v36, v94
	v_mov_b32_e32 v37, v46
	v_pk_mul_f32 v[36:37], v[68:69], v[36:37]
	v_and_b32_e32 v41, 0xffff0000, v116
	v_fma_f32 v36, v19, v95, v36
	v_add_f32_e32 v36, v36, v37
	v_lshlrev_b32_e32 v40, 16, v116
	v_and_b32_e32 v47, 0xffff0000, v120
	v_mul_f32_e32 v36, v36, v41
	v_mul_f32_e32 v35, v35, v40
	v_cvt_pk_bf16_f32 v82, v35, v36
	v_pk_mul_f32 v[36:37], v[22:23], v[46:47]
	v_and_b32_e32 v50, 0xffff0000, v124
	v_fma_f32 v35, v3, v95, v36
	v_add_f32_e32 v35, v35, v37
	v_lshlrev_b32_e32 v40, 16, v113
	v_mul_f32_e32 v35, v35, v50
	v_mov_b32_e32 v50, v106
	v_mov_b32_e32 v51, v40
	v_lshlrev_b32_e32 v36, 16, v121
	v_pk_mul_f32 v[50:51], v[62:63], v[50:51]
	v_mov_b32_e32 v41, v36
	v_fma_f32 v37, v20, v107, v50
	v_add_f32_e32 v37, v37, v51
	v_pk_mul_f32 v[50:51], v[54:55], v[40:41]
	v_mov_b32_e32 v84, v104
	v_fma_f32 v41, v4, v107, v50
	v_and_b32_e32 v50, 0xffff0000, v113
	v_mov_b32_e32 v85, v50
	v_lshlrev_b32_e32 v43, 16, v117
	v_pk_mul_f32 v[84:85], v[64:65], v[84:85]
	v_mul_f32_e32 v37, v37, v43
	v_fma_f32 v43, v21, v105, v84
	v_and_b32_e32 v53, 0xffff0000, v117
	v_lshlrev_b32_e32 v83, 16, v125
	v_add_f32_e32 v41, v41, v51
	v_and_b32_e32 v51, 0xffff0000, v121
	v_add_f32_e32 v43, v43, v85
	v_mul_f32_e32 v41, v41, v83
	v_mul_f32_e32 v43, v43, v53
	v_cvt_pk_bf16_f32 v83, v37, v43
	global_store_dwordx4 v[88:89], v[80:83], off offset:-2048 sc1
	v_and_b32_e32 v96, 0xffff0000, v125
	v_mov_b32_e32 v86, v45
	v_pk_mul_f32 v[80:81], v[24:25], v[50:51]
	v_mov_b32_e32 v84, v49
	v_fma_f32 v37, v5, v105, v80
	v_add_f32_e32 v37, v37, v81
	v_cvt_pk_bf16_f32 v80, v31, v27
	v_cvt_pk_bf16_f32 v81, v33, v29
	v_cvt_pk_bf16_f32 v82, v39, v35
	v_mul_f32_e32 v37, v37, v96
	v_cvt_pk_bf16_f32 v83, v41, v37
	global_store_dwordx4 v[88:89], v[80:83], off sc1
	s_nop 1
	v_mov_b32_e32 v82, v47
	v_mov_b32_e32 v80, v51
	s_cbranch_scc0 .LBB0_219
	s_movk_i32 s2, 0x80
	v_cmp_eq_u32_e32 vcc, s2, v52
	s_and_saveexec_b64 s[2:3], vcc
	v_readlane_b32 s76, v255, 3
	v_readlane_b32 s77, v255, 4
	s_mov_b64 s[74:75], s[28:29]
	s_cbranch_execz .LBB0_215
	v_ashrrev_i32_e32 v43, 31, v42
	v_lshlrev_b64 v[2:3], 13, v[42:43]
	v_lshl_add_u64 v[2:3], s[22:23], 0, v[2:3]
	v_mov_b32_e32 v31, v44
	v_lshl_add_u64 v[2:3], v[2:3], 0, v[0:1]
	s_mov_b64 s[20:21], 0x1000
	v_mov_b32_e32 v33, v48
	v_mov_b32_e32 v39, v46
	v_mov_b32_e32 v41, v50
	v_lshl_add_u64 v[4:5], v[2:3], 0, s[20:21]
	global_store_dwordx4 v[2:3], v[30:33], off sc1
	global_store_dwordx4 v[2:3], v[38:41], off offset:16 sc1
	v_add_co_u32_e32 v2, vcc, 0x1000, v2
	v_mov_b32_e32 v27, v45
	v_mov_b32_e32 v29, v49
	v_addc_co_u32_e32 v3, vcc, 0, v3, vcc
	v_mov_b32_e32 v35, v47
	v_mov_b32_e32 v37, v51
	global_store_dwordx4 v[2:3], v[26:29], off sc1
	global_store_dwordx4 v[4:5], v[34:37], off offset:16 sc1
	s_branch .LBB0_215

.LBB0_225:
	v_ashrrev_i32_e32 v30, 7, v90
	s_waitcnt lgkmcnt(0)
	v_ashrrev_i32_e32 v31, 31, v30
	v_and_b32_e32 v0, 0x3f8, v91
	s_waitcnt vmcnt(0)
	v_lshlrev_b64 v[2:3], 11, v[30:31]
	v_lshl_or_b32 v2, v0, 1, v2
	s_mov_b64 s[20:21], 0x2040000
	v_lshl_add_u64 v[6:7], v[2:3], 0, s[20:21]
	v_lshlrev_b64 v[10:11], 12, v[30:31]
	v_lshlrev_b32_e32 v0, 2, v0
	v_lshl_add_u64 v[2:3], s[22:23], 0, v[6:7]
	v_lshl_add_u64 v[10:11], s[28:29], 0, v[10:11]
	v_lshl_add_u64 v[22:23], s[76:77], 0, v[0:1]
	global_load_dwordx4 v[2:5], v[2:3], off
	v_lshl_add_u64 v[32:33], s[62:63], 0, v[6:7]
	v_lshl_add_u64 v[14:15], v[10:11], 0, v[0:1]
	v_lshl_add_u64 v[26:27], v[22:23], 0, s[38:39]
	v_add_co_u32_e32 v22, vcc, s36, v22
	global_load_dwordx4 v[6:9], v[32:33], off
	global_load_dwordx4 v[10:13], v[14:15], off offset:16
	s_nop 0
	global_load_dwordx4 v[14:17], v[14:15], off
	v_addc_co_u32_e32 v23, vcc, 0, v23, vcc
	global_load_dwordx4 v[22:25], v[22:23], off
	s_nop 0
	global_load_dwordx4 v[26:29], v[26:27], off offset:16
	v_add_u32_e32 v90, s25, v90
	v_cmp_lt_i32_e32 vcc, s35, v90
	v_add_u32_e32 v91, s33, v91
	s_or_b64 s[2:3], vcc, s[2:3]
	s_waitcnt vmcnt(5)
	v_and_b32_e32 v19, 0xffff0000, v2
	v_lshlrev_b32_e32 v20, 16, v3
	v_and_b32_e32 v21, 0xffff0000, v3
	v_and_b32_e32 v3, 0xffff0000, v4
	v_lshlrev_b32_e32 v18, 16, v2
	v_lshlrev_b32_e32 v2, 16, v4
	s_waitcnt vmcnt(4)
	v_lshlrev_b32_e32 v34, 16, v6
	v_and_b32_e32 v6, 0xffff0000, v6
	v_lshlrev_b32_e32 v4, 16, v5
	s_waitcnt vmcnt(1)
	v_fma_f32 v15, v23, v19, v15
	v_mul_f32_e32 v6, v15, v6
	v_lshlrev_b32_e32 v15, 16, v7
	v_fma_f32 v16, v24, v20, v16
	v_and_b32_e32 v5, 0xffff0000, v5
	v_mul_f32_e32 v15, v16, v15
	v_and_b32_e32 v7, 0xffff0000, v7
	v_fmac_f32_e32 v17, v25, v21
	v_lshlrev_b32_e32 v16, 16, v8
	v_and_b32_e32 v8, 0xffff0000, v8
	s_waitcnt vmcnt(0)
	v_fma_f32 v11, v27, v3, v11
	v_fma_f32 v14, v22, v18, v14
	v_mul_f32_e32 v7, v17, v7
	v_mul_f32_e32 v8, v11, v8
	v_lshlrev_b32_e32 v11, 16, v9
	v_and_b32_e32 v9, 0xffff0000, v9
	v_fmac_f32_e32 v13, v29, v5
	v_mul_f32_e32 v14, v14, v34
	v_fma_f32 v10, v26, v2, v10
	v_fma_f32 v12, v28, v4, v12
	v_mul_f32_e32 v9, v13, v9
	v_cvt_pk_bf16_f32 v6, v14, v6
	v_cvt_pk_bf16_f32 v7, v15, v7
	v_mul_f32_e32 v10, v10, v16
	v_mul_f32_e32 v11, v12, v11
	v_cvt_pk_bf16_f32 v8, v10, v8
	v_cvt_pk_bf16_f32 v9, v11, v9
	global_store_dwordx4 v[32:33], v[6:9], off sc1
	s_nop 1
	v_lshlrev_b64 v[6:7], 13, v[30:31]
	v_lshl_add_u64 v[6:7], s[30:31], 0, v[6:7]
	v_lshl_add_u64 v[6:7], v[6:7], 0, v[0:1]
	global_store_dwordx4 v[6:7], v[18:21], off sc1
	global_store_dwordx4 v[6:7], v[2:5], off offset:16 sc1
	s_andn2_b64 exec, exec, s[2:3]
	s_cbranch_execnz .LBB0_225

.LBB0_337:
	v_mad_i64_i32 v[2:3], s[22:23], v2, s33, 0
	v_lshl_add_u64 v[2:3], v[2:3], 1, s[0:1]
	s_ashr_i32 s43, s42, 31
	v_lshl_add_u64 v[2:3], s[42:43], 1, v[2:3]
	v_lshlrev_b32_e32 v0, 1, v20
	v_lshl_add_u64 v[2:3], v[2:3], 0, v[0:1]
	global_store_dwordx4 v[2:3], v[12:15], off sc1
	v_mov_b64_e32 v[18:19], v[6:7]
	s_add_i32 s40, s40, s68
	v_mov_b64_e32 v[14:15], v[10:11]
	s_and_b64 vcc, exec, s[38:39]
	v_mov_b64_e32 v[16:17], v[4:5]
	v_mov_b64_e32 v[12:13], v[8:9]
	s_mov_b64 s[0:1], s[30:31]
	s_mov_b64 s[36:37], s[28:29]
	s_mov_b32 s33, s45
	s_mov_b32 s42, s20
	s_mov_b32 s35, s44
	s_mov_b32 s46, s64
	s_barrier
	s_cbranch_vccnz .LBB0_370

.LBB0_386:
	v_ashrrev_i32_e32 v3, 31, v2
	v_lshlrev_b64 v[2:3], 11, v[2:3]
	v_lshl_add_u64 v[2:3], s[0:1], 0, v[2:3]
	s_ashr_i32 s43, s42, 31
	v_lshl_add_u64 v[2:3], s[42:43], 1, v[2:3]
	v_lshlrev_b32_e32 v0, 1, v20
	v_lshl_add_u64 v[2:3], v[2:3], 0, v[0:1]
	global_store_dwordx4 v[2:3], v[12:15], off sc1
	v_readlane_b32 s0, v250, 63
	v_mov_b64_e32 v[18:19], v[6:7]
	v_mov_b64_e32 v[14:15], v[10:11]
	s_add_i32 s33, s33, s0
	s_and_b64 vcc, exec, s[38:39]
	v_mov_b64_e32 v[16:17], v[4:5]
	v_mov_b64_e32 v[12:13], v[8:9]
	s_mov_b64 s[0:1], s[36:37]
	s_mov_b64 s[2:3], s[30:31]
	s_mov_b32 s42, s28
	s_mov_b32 s40, s41
	s_mov_b32 s45, s44
	s_barrier
	s_cbranch_vccnz .LBB0_423

.LBB0_452:
	v_mad_i64_i32 v[2:3], s[22:23], v2, s33, 0
	v_lshl_add_u64 v[2:3], v[2:3], 1, s[0:1]
	s_ashr_i32 s39, s38, 31
	v_lshl_add_u64 v[2:3], s[38:39], 1, v[2:3]
	v_lshlrev_b32_e32 v0, 1, v20
	v_lshl_add_u64 v[2:3], v[2:3], 0, v[0:1]
	global_store_dwordx4 v[2:3], v[12:15], off sc1
	v_mov_b64_e32 v[18:19], v[6:7]
	s_cmpk_lt_i32 s35, 0x840
	v_mov_b64_e32 v[14:15], v[10:11]
	v_mov_b64_e32 v[16:17], v[4:5]
	v_mov_b64_e32 v[12:13], v[8:9]
	s_mov_b64 s[0:1], s[30:31]
	s_mov_b64 s[36:37], s[20:21]
	s_mov_b32 s33, s45
	s_mov_b32 s43, s28
	s_mov_b32 s40, s44
	s_mov_b32 s42, s41
	s_barrier
	s_cbranch_scc0 .LBB0_484

.LBB0_488:
	s_or_b64 exec, exec, s[2:3]
	v_ashrrev_i32_e32 v3, 31, v2
	v_lshlrev_b64 v[2:3], 11, v[2:3]
	v_lshl_add_u64 v[2:3], s[44:45], 0, v[2:3]
	s_ashr_i32 s1, s0, 31
	v_lshl_add_u64 v[2:3], s[0:1], 1, v[2:3]
	v_lshlrev_b32_e32 v0, 1, v20
	v_lshl_add_u64 v[2:3], v[2:3], 0, v[0:1]
	global_store_dwordx4 v[2:3], v[12:15], off sc1
	s_add_i32 s28, s28, s25
	v_mov_b64_e32 v[18:19], v[10:11]
	v_mov_b64_e32 v[14:15], v[6:7]
	s_cmpk_gt_i32 s28, 0x43f
	v_mov_b64_e32 v[12:13], v[4:5]
	v_mov_b64_e32 v[16:17], v[8:9]
	s_mov_b32 s2, s29
	s_barrier
	s_cbranch_scc1 .LBB0_503

.LBB0_524:
	s_or_b64 exec, exec, s[2:3]
	v_cvt_f32_u32_e32 v5, v3
	s_waitcnt vmcnt(0)
	v_readfirstlane_b32 s2, v4
	v_sub_u32_e32 v4, 0, v3
	v_rcp_iflag_f32_e32 v5, v5
	v_add_u32_e32 v6, s2, v0
	v_mul_f32_e32 v5, 0x4f7ffffe, v5
	v_cvt_u32_f32_e32 v5, v5
	v_mul_lo_u32 v0, v4, v5
	v_mul_hi_u32 v0, v5, v0
	v_add_u32_e32 v0, v5, v0
	v_mul_hi_u32 v0, v6, v0
	v_mul_lo_u32 v4, v0, v3
	v_sub_u32_e32 v4, v6, v4
	v_add_u32_e32 v5, 1, v0
	v_cmp_ge_u32_e32 vcc, v4, v3
	s_nop 1
	v_cndmask_b32_e32 v0, v0, v5, vcc
	v_sub_u32_e32 v5, v4, v3
	v_cndmask_b32_e32 v4, v4, v5, vcc
	v_add_u32_e32 v5, 1, v0
	v_cmp_ge_u32_e32 vcc, v4, v3
	v_add_u32_e32 v4, 1, v6
	s_nop 0
	v_cndmask_b32_e32 v0, v0, v5, vcc
	v_mul_lo_u32 v5, v3, v0
	v_add_u32_e32 v3, v5, v3
	v_cmp_ne_u32_e32 vcc, v4, v3
	s_cbranch_vccnz .Lxb_poll
	s_cmp_eq_u32 s41, 1
	s_cbranch_scc1 .Lxb_wb
	s_cmp_eq_u32 s41, 7
	s_cbranch_scc1 .Lxb_wb
	s_cmp_eq_u32 s41, 11
	s_cbranch_scc1 .Lxb_wb
	s_cmp_eq_u32 s41, 21
	s_cbranch_scc0 .Lxb_nowb
.Lxb_wb:
	buffer_wbl2 sc1
